# LN phase: row 1's x and Y lines touched while row 0's loads are in flight
# baseline (speedup 1.0000x reference)
.LBB0_71:
	v_add_u32_e32 v230, s4, v130
	v_min_i32_e32 v230, s15, v230
	v_mul_hi_i32 v231, v230, s30
	v_lshrrev_b32_e32 v233, 31, v231
	v_ashrrev_i32_e32 v231, 9, v231
	v_add_u32_e32 v231, v231, v233
	v_mul_i32_i24_e32 v233, 0x900, v231
	v_sub_u32_e32 v232, v230, v233
	s_movk_i32 s62, 0x100
	v_cmp_gt_i32_e64 s[60:61], s62, v232
	v_mov_b32_e32 v234, s13
	v_mov_b32_e32 v235, s12
	v_mov_b32_e32 v238, s11
	v_mov_b32_e32 v239, s10
	v_cndmask_b32_e64 v234, v234, v238, s[60:61]
	v_cndmask_b32_e64 v235, v235, v239, s[60:61]
	v_cndmask_b32_e64 v233, 23, 20, s[60:61]
	v_lshlrev_b32_e32 v236, v233, v231
	v_add_u32_e32 v233, 0xffffff00, v232
	v_cndmask_b32_e64 v233, v233, v232, s[60:61]
	v_lshl_add_u32 v236, v233, 12, v236
	v_lshl_add_u32 v236, v176, 2, v236
	v_mov_b32_e32 v237, 0
	v_lshl_add_u64 v[234:235], v[234:235], 0, v[236:237]
	global_load_dword v244, v[234:235], off
	v_lshlrev_b32_e32 v248, 11, v230
	v_lshrrev_b32_e32 v233, 1, v176
	v_add3_u32 v248, v248, v176, v233
	v_mov_b32_e32 v249, 0
	v_lshl_add_u64 v[246:247], v[142:143], 0, v[248:249]
	global_load_dword v245, v[246:247], off
	s_waitcnt vmcnt(0) lgkmcnt(0)
	v_lshlrev_b32_e32 v146, 16, v152
	v_and_b32_e32 v147, 0xffff0000, v152
	v_pk_mul_f32 v[102:103], v[102:103], v[146:147]
	s_mov_b32 s0, 0x3fd744fd
	v_pk_fma_f32 v[146:147], v[98:99], s[0:1], v[102:103] op_sel_hi:[1,0,1]
	v_lshlrev_b32_e32 v98, 16, v153
	v_and_b32_e32 v99, 0xffff0000, v153
	v_pk_mul_f32 v[98:99], v[104:105], v[98:99]
	v_add_f32_e32 v0, v146, v147
	v_pk_fma_f32 v[152:153], v[100:101], s[0:1], v[98:99] op_sel_hi:[1,0,1]
	v_lshlrev_b32_e32 v98, 16, v160
	v_and_b32_e32 v99, 0xffff0000, v160
	v_pk_mul_f32 v[98:99], v[114:115], v[98:99]
	v_add_f32_e32 v0, v152, v0
	v_pk_fma_f32 v[154:155], v[106:107], s[0:1], v[98:99] op_sel_hi:[1,0,1]
	v_lshlrev_b32_e32 v98, 16, v161
	v_and_b32_e32 v99, 0xffff0000, v161
	v_pk_mul_f32 v[98:99], v[116:117], v[98:99]
	v_add_f32_e32 v0, v153, v0
	v_pk_fma_f32 v[160:161], v[108:109], s[0:1], v[98:99] op_sel_hi:[1,0,1]
	v_add_f32_e32 v98, v154, v155
	v_add_f32_e32 v98, v160, v98
	v_add_f32_e32 v0, 0, v0
	v_add_f32_e32 v98, v161, v98
	v_add_f32_e32 v0, v0, v98
	v_lshlrev_b32_e32 v98, 16, v168
	v_and_b32_e32 v99, 0xffff0000, v168
	v_pk_mul_f32 v[98:99], v[122:123], v[98:99]
	s_nop 0
	v_pk_fma_f32 v[164:165], v[110:111], s[0:1], v[98:99] op_sel_hi:[1,0,1]
	v_lshlrev_b32_e32 v98, 16, v169
	v_and_b32_e32 v99, 0xffff0000, v169
	v_pk_mul_f32 v[98:99], v[124:125], v[98:99]
	s_nop 0
	v_pk_fma_f32 v[168:169], v[112:113], s[0:1], v[98:99] op_sel_hi:[1,0,1]
	v_add_f32_e32 v98, v164, v165
	v_add_f32_e32 v98, v168, v98
	v_add_f32_e32 v98, v169, v98
	v_add_f32_e32 v0, v0, v98
	v_lshlrev_b32_e32 v98, 16, v174
	v_and_b32_e32 v99, 0xffff0000, v174
	v_pk_mul_f32 v[98:99], v[126:127], v[98:99]
	s_nop 0
	v_pk_fma_f32 v[172:173], v[118:119], s[0:1], v[98:99] op_sel_hi:[1,0,1]
	v_lshlrev_b32_e32 v98, 16, v175
	v_and_b32_e32 v99, 0xffff0000, v175
	v_pk_mul_f32 v[98:99], v[128:129], v[98:99]
	s_nop 0
	v_pk_fma_f32 v[174:175], v[120:121], s[0:1], v[98:99] op_sel_hi:[1,0,1]
	v_add_f32_e32 v98, v172, v173
	v_add_f32_e32 v98, v174, v98
	v_add_f32_e32 v98, v175, v98
	v_add_f32_e32 v0, v0, v98
